# v24 + mLSTM step 2: the four 8-deep MFMA chains read their A fragments into rotating register quads with counted waits instead of one quad with a full wait per MFMA
# speedup vs baseline: 1.0060x; 1.0060x over previous
; DI unsigned pk2(float a, float b) { f32x2 v = {a, b}; hbf2 r = __builtin_convertvector(v, hbf2); return __builtin_bit_cast(unsigned, r); }
; DI float bf2f(bf16_t b) { return __uint_as_float(((unsigned)b) << 16); }
; DI void mlstm_unit(const Params& p, unsigned char* smem, int unit) {
;     ...
; #pragma unroll
;         for (int i = 0; i < 4; ++i) {
;             const int task = tid + 512 * i, k = task & 255, s0 = (task >> 8) * 8;
;             float v[8];
;             const f32x4 wa = *(const f32x4*)(sws + s0), wb = *(const f32x4*)(sws + s0 + 4);
; #pragma unroll
;             for (int e = 0; e < 4; ++e) { v[e] = bf2f(sK[(s0 + e) * 264 + k]) * wa[e]; v[4 + e] = bf2f(sK[(s0 + 4 + e) * 264 + k]) * wb[e]; }
;             u32x4 w; w.x = pk2(v[0], v[1]); w.y = pk2(v[2], v[3]); w.z = pk2(v[4], v[5]); w.w = pk2(v[6], v[7]);
;             *(u32x4*)(sKwt + k * 72 + s0) = w;
;         }
;         f32x4 accH[2];
;         {
;             bf16x8 Bq[8];
; #pragma unroll
;             for (int ks = 0; ks < 8; ++ks) Bq[ks] = *(const bf16x8*)(sQ + (ti * 16 + fr) * 264 + ks * 32 + fq * 8);
;             const int t = ti * 16 + fr;
;             const float Mt_t = sMt[t];
.LBB0_381:
	s_and_b32 s39, 1, s96
	s_cselect_b32 s72, 0, 0x540
	s_add_i32 s82, s72, 0
	s_add_i32 s82, s82, 0x26800
	v_lshl_add_u32 v72, v160, 2, s82
	ds_read_b128 v[68:71], v72 offset:1024
	ds_read_b128 v[72:75], v72 offset:1040
	ds_read_u16 v76, v161 offset:33792
	ds_read_u16 v77, v161 offset:34320
	ds_read_u16 v78, v162 offset:35904
	ds_read_u16 v79, v162 offset:36432
	ds_read_u16 v80, v161 offset:34848
	ds_read_u16 v81, v162 offset:36960
	ds_read_u16 v82, v162 offset:37488
	ds_read_u16 v83, v161 offset:35376
	s_waitcnt lgkmcnt(6)
	v_lshlrev_b32_e32 v77, 16, v77
	v_lshlrev_b32_e32 v76, 16, v76
	v_pk_mul_f32 v[68:69], v[68:69], v[76:77]
	s_waitcnt lgkmcnt(4)
	v_lshlrev_b32_e32 v77, 16, v79
	v_lshlrev_b32_e32 v76, 16, v78
	v_pk_mul_f32 v[72:73], v[72:73], v[76:77]
	s_waitcnt lgkmcnt(0)
	v_lshlrev_b32_e32 v77, 16, v83
	v_lshlrev_b32_e32 v76, 16, v80
	v_pk_mul_f32 v[70:71], v[70:71], v[76:77]
	v_lshlrev_b32_e32 v77, 16, v82
	v_lshlrev_b32_e32 v76, 16, v81
	v_pk_mul_f32 v[74:75], v[74:75], v[76:77]
	v_cvt_pk_bf16_f32 v68, v68, v69
	v_cvt_pk_bf16_f32 v69, v70, v71
	v_cvt_pk_bf16_f32 v70, v72, v73
	v_cvt_pk_bf16_f32 v71, v74, v75
	ds_write_b128 v163, v[68:71]
	v_lshl_add_u32 v72, v164, 2, s82
	ds_read_b128 v[68:71], v72 offset:1024
	ds_read_b128 v[72:75], v72 offset:1040
	ds_read_u16 v76, v165 offset:33792
	ds_read_u16 v77, v165 offset:34320
	ds_read_u16 v78, v166 offset:35904
	ds_read_u16 v79, v166 offset:36432
	ds_read_u16 v80, v165 offset:34848
	ds_read_u16 v81, v166 offset:36960
	ds_read_u16 v82, v166 offset:37488
	ds_read_u16 v83, v165 offset:35376
	s_waitcnt lgkmcnt(6)
	v_lshlrev_b32_e32 v77, 16, v77
	v_lshlrev_b32_e32 v76, 16, v76
	v_pk_mul_f32 v[68:69], v[68:69], v[76:77]
	s_waitcnt lgkmcnt(4)
	v_lshlrev_b32_e32 v77, 16, v79
	v_lshlrev_b32_e32 v76, 16, v78
	v_pk_mul_f32 v[72:73], v[72:73], v[76:77]
	s_waitcnt lgkmcnt(0)
	v_lshlrev_b32_e32 v77, 16, v83
	v_lshlrev_b32_e32 v76, 16, v80
	v_pk_mul_f32 v[70:71], v[70:71], v[76:77]
	v_lshlrev_b32_e32 v77, 16, v82
	v_lshlrev_b32_e32 v76, 16, v81
	v_pk_mul_f32 v[74:75], v[74:75], v[76:77]
	v_cvt_pk_bf16_f32 v68, v68, v69
	v_cvt_pk_bf16_f32 v69, v70, v71
	v_cvt_pk_bf16_f32 v70, v72, v73
	v_cvt_pk_bf16_f32 v71, v74, v75
	ds_write_b128 v167, v[68:71]
	v_lshl_add_u32 v72, v168, 2, s82
	ds_read_b128 v[68:71], v72 offset:1024
	ds_read_b128 v[72:75], v72 offset:1040
	ds_read_u16 v76, v169 offset:33792
	ds_read_u16 v77, v169 offset:34320
	ds_read_u16 v78, v170 offset:35904
	ds_read_u16 v79, v170 offset:36432
	ds_read_u16 v80, v169 offset:34848
	ds_read_u16 v81, v170 offset:36960
	ds_read_u16 v82, v170 offset:37488
	ds_read_u16 v83, v169 offset:35376
	s_waitcnt lgkmcnt(6)
	v_lshlrev_b32_e32 v77, 16, v77
	v_lshlrev_b32_e32 v76, 16, v76
	v_pk_mul_f32 v[68:69], v[68:69], v[76:77]
	s_waitcnt lgkmcnt(4)
	v_lshlrev_b32_e32 v77, 16, v79
	v_lshlrev_b32_e32 v76, 16, v78
	v_pk_mul_f32 v[72:73], v[72:73], v[76:77]
	s_waitcnt lgkmcnt(0)
	v_lshlrev_b32_e32 v77, 16, v83
	v_lshlrev_b32_e32 v76, 16, v80
	v_pk_mul_f32 v[70:71], v[70:71], v[76:77]
	v_lshlrev_b32_e32 v77, 16, v82
	v_lshlrev_b32_e32 v76, 16, v81
	v_pk_mul_f32 v[74:75], v[74:75], v[76:77]
	v_cvt_pk_bf16_f32 v68, v68, v69
	v_cvt_pk_bf16_f32 v69, v70, v71
	v_cvt_pk_bf16_f32 v70, v72, v73
	v_cvt_pk_bf16_f32 v71, v74, v75
	ds_write_b128 v171, v[68:71]
	v_lshl_add_u32 v72, v172, 2, s82
	ds_read_b128 v[68:71], v72 offset:1024
	ds_read_b128 v[72:75], v72 offset:1040
	ds_read_u16 v76, v173 offset:33792
	ds_read_u16 v77, v173 offset:34320
	ds_read_u16 v78, v174 offset:35904
	ds_read_u16 v79, v174 offset:36432
	ds_read_u16 v80, v173 offset:34848
	ds_read_u16 v81, v174 offset:36960
	ds_read_u16 v82, v174 offset:37488
	ds_read_u16 v83, v173 offset:35376
	s_waitcnt lgkmcnt(6)
	v_lshlrev_b32_e32 v77, 16, v77
	v_lshlrev_b32_e32 v76, 16, v76
	v_pk_mul_f32 v[68:69], v[68:69], v[76:77]
	s_waitcnt lgkmcnt(4)
	v_lshlrev_b32_e32 v77, 16, v79
	v_lshlrev_b32_e32 v76, 16, v78
	v_pk_mul_f32 v[72:73], v[72:73], v[76:77]
	s_waitcnt lgkmcnt(0)
	v_lshlrev_b32_e32 v77, 16, v83
	v_lshlrev_b32_e32 v76, 16, v80
	v_pk_mul_f32 v[70:71], v[70:71], v[76:77]
	v_lshlrev_b32_e32 v77, 16, v82
	v_lshlrev_b32_e32 v76, 16, v81
	v_pk_mul_f32 v[74:75], v[74:75], v[76:77]
	v_cvt_pk_bf16_f32 v68, v68, v69
	v_cvt_pk_bf16_f32 v69, v70, v71
	v_cvt_pk_bf16_f32 v70, v72, v73
	v_cvt_pk_bf16_f32 v71, v74, v75
	ds_write_b128 v176, v[68:71]
	ds_read_b128 v[92:95], v190 offset:64
	ds_read_b128 v[88:91], v190 offset:128
	ds_read_b128 v[84:87], v190 offset:192
	ds_read_b128 v[80:83], v190 offset:256
	ds_read_b128 v[76:79], v190 offset:320
	ds_read_b128 v[72:75], v190 offset:384
	ds_read_b128 v[68:71], v190 offset:448
	v_lshl_add_u32 v200, v144, 2, s82
	ds_read_b128 v[96:99], v190
	ds_read_b32 v201, v200 offset:256
	v_lshl_add_u32 v202, v147, 2, s82
	s_and_saveexec_b64 s[72:73], s[14:15]
	s_xor_b64 vcc, exec, s[72:73]
	s_cbranch_execz .LBB0_389
; DI unsigned pk2(float a, float b) { f32x2 v = {a, b}; hbf2 r = __builtin_convertvector(v, hbf2); return __builtin_bit_cast(unsigned, r); }
; DI float sum_x16_x32(float x) { return sum_x32(sum_x16(x)); }
; DI f32x4 mfma16(bf16x8 a, bf16x8 b, f32x4 c) { return __builtin_amdgcn_mfma_f32_16x16x32_bf16(a, b, c, 0, 0, 0); }
; DI void mlstm_unit(const Params& p, unsigned char* smem, int unit) {
;     ...
;                 f32x4 aS = (f32x4){0.f, 0.f, 0.f, 0.f};
; #pragma unroll
;                 for (int ks = 0; ks < 8; ++ks) aS = mfma16(*(const bf16x8*)(sK + (si * 16 + fr) * 264 + ks * 32 + fq * 8), Bq[ks], aS);
;                 float val[4]; float ps = 0.f;
;                 const f32x4 gv = *(const f32x4*)(sg + si * 16 + fq * 4);
; #pragma unroll
;                 for (int j = 0; j < 4; ++j) {
;                     const int s = si * 16 + fq * 4 + j;
;                     const float e = __expf(fminf(gv[j] - Mt_t, 0.f));
;                     const float d = (s <= t) ? e : 0.f;
;                     val[j] = aS[j] * d; ps += val[j];
;                 }
;                 ps = sum_x16_x32(ps);
;                 if (fq == 0) srs[si * 64 + t] = ps;
;                 u32x2 w; w.x = pk2(val[0], val[1]); w.y = pk2(val[2], val[3]);
;                 *(u32x2*)(sSd + t * 72 + si * 16 + fq * 4) = w;
;             }
	v_add_u32_e32 v203, v149, v177
	ds_read_b128 v[208:211], v203 offset:33792
	ds_read_b128 v[212:215], v203 offset:33856
	ds_read_b128 v[216:219], v203 offset:33920
	ds_read_b128 v[220:223], v203 offset:33984
	ds_read_b128 v[224:227], v203 offset:34048
	s_waitcnt lgkmcnt(4)
	v_mfma_f32_16x16x32_bf16 v[100:103], v[208:211], v[96:99], 0
	ds_read_b128 v[208:211], v203 offset:34112
	s_waitcnt lgkmcnt(4)
	v_mfma_f32_16x16x32_bf16 v[100:103], v[212:215], v[92:95], v[100:103]
	ds_read_b128 v[212:215], v203 offset:34176
	s_waitcnt lgkmcnt(4)
	v_mfma_f32_16x16x32_bf16 v[100:103], v[216:219], v[88:91], v[100:103]
	ds_read_b128 v[216:219], v203 offset:34240
	v_lshl_add_u32 v203, v146, 2, v202
	s_waitcnt lgkmcnt(4)
	v_mfma_f32_16x16x32_bf16 v[100:103], v[220:223], v[84:87], v[100:103]
	s_waitcnt lgkmcnt(3)
	v_mfma_f32_16x16x32_bf16 v[100:103], v[224:227], v[80:83], v[100:103]
	s_waitcnt lgkmcnt(2)
	v_mfma_f32_16x16x32_bf16 v[100:103], v[208:211], v[76:79], v[100:103]
	ds_read_b128 v[208:211], v203
	s_waitcnt lgkmcnt(2)
	v_mfma_f32_16x16x32_bf16 v[100:103], v[212:215], v[72:75], v[100:103]
	s_waitcnt lgkmcnt(1)
	v_mfma_f32_16x16x32_bf16 v[100:103], v[216:219], v[68:71], v[100:103]
	s_waitcnt lgkmcnt(0)
	v_sub_f32_e32 v203, v208, v201
	v_sub_f32_e32 v204, v209, v201
	v_min_f32_e32 v203, 0, v203
	v_min_f32_e32 v204, 0, v204
	v_mul_f32_e32 v203, 0x3fb8aa3b, v203
	v_mul_f32_e32 v204, 0x3fb8aa3b, v204
	v_exp_f32_e32 v203, v203
	v_exp_f32_e32 v204, v204
	s_nop 0
	v_cndmask_b32_e64 v205, 0, v204, s[18:19]
	v_cndmask_b32_e64 v204, v203, 0, s[16:17]
	v_pk_mul_f32 v[100:101], v[100:101], v[204:205]
	v_sub_f32_e32 v204, v210, v201
	v_sub_f32_e32 v205, v211, v201
	v_min_f32_e32 v204, 0, v204
	v_min_f32_e32 v205, 0, v205
	v_mul_f32_e32 v204, 0x3fb8aa3b, v204
	v_mul_f32_e32 v205, 0x3fb8aa3b, v205
	v_exp_f32_e32 v204, v204
	v_exp_f32_e32 v205, v205
	v_add_f32_e32 v203, 0, v100
	v_add_f32_e32 v203, v101, v203
	v_cndmask_b32_e64 v204, v204, 0, s[22:23]
	v_cndmask_b32_e64 v205, v205, 0, s[20:21]
	v_pk_mul_f32 v[102:103], v[102:103], v[204:205]
	s_nop 0
	v_add_f32_e32 v203, v102, v203
	v_add_f32_e32 v203, v103, v203
	v_mov_b32_e32 v204, v203
	s_nop 1
	v_permlane16_swap_b32_e32 v203, v204
	v_add_f32_e32 v203, v203, v204
	v_mov_b32_e32 v204, v203
	s_nop 1
	v_permlane32_swap_b32_e32 v203, v204
	s_and_saveexec_b64 s[72:73], s[8:9]
	v_add_f32_e32 v203, v203, v204
	v_add_u32_e32 v204, v148, v179
	ds_write_b32 v204, v203
	s_or_b64 exec, exec, s[72:73]
	v_cvt_pk_bf16_f32 v100, v100, v101
	v_cvt_pk_bf16_f32 v101, v102, v103
	ds_write_b64 v180, v[100:101]
	s_andn2_saveexec_b64 s[72:73], vcc
	s_cbranch_execnz .LBB0_390

; DI unsigned pk2(float a, float b) { f32x2 v = {a, b}; hbf2 r = __builtin_convertvector(v, hbf2); return __builtin_bit_cast(unsigned, r); }
; DI float sum_x16_x32(float x) { return sum_x32(sum_x16(x)); }
; DI f32x4 mfma16(bf16x8 a, bf16x8 b, f32x4 c) { return __builtin_amdgcn_mfma_f32_16x16x32_bf16(a, b, c, 0, 0, 0); }
; DI void mlstm_unit(const Params& p, unsigned char* smem, int unit) {
;     ...
;                 f32x4 aS = (f32x4){0.f, 0.f, 0.f, 0.f};
; #pragma unroll
;                 for (int ks = 0; ks < 8; ++ks) aS = mfma16(*(const bf16x8*)(sK + (si * 16 + fr) * 264 + ks * 32 + fq * 8), Bq[ks], aS);
;                 float val[4]; float ps = 0.f;
;                 const f32x4 gv = *(const f32x4*)(sg + si * 16 + fq * 4);
; #pragma unroll
;                 for (int j = 0; j < 4; ++j) {
;                     const int s = si * 16 + fq * 4 + j;
;                     const float e = __expf(fminf(gv[j] - Mt_t, 0.f));
;                     const float d = (s <= t) ? e : 0.f;
;                     val[j] = aS[j] * d; ps += val[j];
;                 }
;                 ps = sum_x16_x32(ps);
;                 if (fq == 0) srs[si * 64 + t] = ps;
;                 u32x2 w; w.x = pk2(val[0], val[1]); w.y = pk2(val[2], val[3]);
;                 *(u32x2*)(sSd + t * 72 + si * 16 + fq * 4) = w;
;             }
.LBB0_394:
	ds_read_b128 v[208:211], v192 offset:33792
	ds_read_b128 v[212:215], v192 offset:33856
	v_lshl_add_u32 v202, v118, 2, v202
	ds_read_b128 v[216:219], v192 offset:33920
	ds_read_b128 v[220:223], v192 offset:33984
	ds_read_b128 v[224:227], v192 offset:34048
	ds_read_b128 v[202:205], v202
	s_waitcnt lgkmcnt(5)
	v_mfma_f32_16x16x32_bf16 v[100:103], v[208:211], v[96:99], 0
	ds_read_b128 v[208:211], v192 offset:34112
	s_waitcnt lgkmcnt(5)
	v_mfma_f32_16x16x32_bf16 v[100:103], v[212:215], v[92:95], v[100:103]
	ds_read_b128 v[212:215], v192 offset:34176
	s_waitcnt lgkmcnt(5)
	v_mfma_f32_16x16x32_bf16 v[100:103], v[216:219], v[88:91], v[100:103]
	ds_read_b128 v[216:219], v192 offset:34240
	s_waitcnt lgkmcnt(5)
	v_mfma_f32_16x16x32_bf16 v[100:103], v[220:223], v[84:87], v[100:103]
	s_waitcnt lgkmcnt(4)
	v_mfma_f32_16x16x32_bf16 v[100:103], v[224:227], v[80:83], v[100:103]
	s_waitcnt lgkmcnt(3)
	v_sub_f32_e32 v202, v202, v201
	v_sub_f32_e32 v203, v203, v201
	v_min_f32_e32 v202, 0, v202
	v_min_f32_e32 v203, 0, v203
	v_mul_f32_e32 v202, 0x3fb8aa3b, v202
	v_mul_f32_e32 v203, 0x3fb8aa3b, v203
	v_exp_f32_e32 v202, v202
	v_exp_f32_e32 v203, v203
	s_waitcnt lgkmcnt(2)
	v_mfma_f32_16x16x32_bf16 v[100:103], v[208:211], v[76:79], v[100:103]
	v_cndmask_b32_e64 v203, 0, v203, s[28:29]
	v_cndmask_b32_e64 v202, v202, 0, s[26:27]
	s_waitcnt lgkmcnt(1)
	v_mfma_f32_16x16x32_bf16 v[100:103], v[212:215], v[72:75], v[100:103]
	s_waitcnt lgkmcnt(0)
	v_mfma_f32_16x16x32_bf16 v[100:103], v[216:219], v[68:71], v[100:103]
	s_nop 7
	v_pk_mul_f32 v[100:101], v[100:101], v[202:203]
	s_nop 0
	v_add_f32_e32 v202, 0, v100
	v_add_f32_e32 v208, v101, v202
	v_sub_f32_e32 v202, v204, v201
	v_sub_f32_e32 v201, v205, v201
	v_min_f32_e32 v202, 0, v202
	v_min_f32_e32 v201, 0, v201
	v_mul_f32_e32 v202, 0x3fb8aa3b, v202
	v_mul_f32_e32 v201, 0x3fb8aa3b, v201
	v_exp_f32_e32 v202, v202
	v_exp_f32_e32 v201, v201
	v_cndmask_b32_e64 v202, v202, 0, s[34:35]
	v_cndmask_b32_e64 v203, v201, 0, s[30:31]
	v_pk_mul_f32 v[102:103], v[102:103], v[202:203]
	s_nop 0
	v_add_f32_e32 v201, v102, v208
	v_add_f32_e32 v201, v103, v201
	v_mov_b32_e32 v202, v201
	s_nop 1
	v_permlane16_swap_b32_e32 v201, v202
	v_add_f32_e32 v201, v201, v202
	v_mov_b32_e32 v202, v201
	s_nop 1
	v_permlane32_swap_b32_e32 v201, v202
	s_and_saveexec_b64 s[72:73], s[8:9]
	v_add_f32_e32 v201, v201, v202
	v_add_u32_e32 v202, v148, v181
	ds_write_b32 v202, v201
	s_or_b64 exec, exec, s[72:73]
	v_cvt_pk_bf16_f32 v100, v100, v101
	v_cvt_pk_bf16_f32 v101, v102, v103
	v_add_u32_e32 v102, v150, v182
	ds_write_b64 v102, v[100:101]
; DI float bflo(unsigned u) { return __uint_as_float(u << 16); }
; DI float bfhi(unsigned u) { return __uint_as_float(u & 0xffff0000u); }
; DI f32x4 mfma16(bf16x8 a, bf16x8 b, f32x4 c) { return __builtin_amdgcn_mfma_f32_16x16x32_bf16(a, b, c, 0, 0, 0); }
; DI void mlstm_unit(const Params& p, unsigned char* smem, int unit) {
;     ...
; #pragma unroll
;             for (int x = 0; x < 2; ++x) {
;                 const int vi = pi + x;
;                 f32x4 aH = (f32x4){0.f, 0.f, 0.f, 0.f};
; #pragma unroll
;                 for (int ks = 0; ks < 8; ++ks) aH = mfma16(*(const bf16x8*)(sCb + (vi * 16 + fr) * 264 + ks * 32 + fq * 8), Bq[ks], aH);
;                 accH[x] = aH;
;             }
;         }
;         {
;             const int t = tid >> 3, part = tid & 7;
;             float s = 0.f;
; #pragma unroll
;             for (int i = 0; i < 4; ++i) {
;                 const u32x4 qv = *(const u32x4*)(sQ + t * 264 + part * 32 + i * 8);
;                 const f32x4 na = *(const f32x4*)(sN + part * 32 + i * 8), nb = *(const f32x4*)(sN + part * 32 + i * 8 + 4);
;                 s += bflo(qv.x) * na[0] + bfhi(qv.x) * na[1] + bflo(qv.y) * na[2] + bfhi(qv.y) * na[3]
;                    + bflo(qv.z) * nb[0] + bfhi(qv.z) * nb[1] + bflo(qv.w) * nb[2] + bfhi(qv.w) * nb[3];
;             }
;             s += __shfl_xor(s, 1); s += __shfl_xor(s, 2); s += __shfl_xor(s, 4);
;             if (part == 0) snq[t] = s;
;         }
.LBB0_397:
	s_or_b64 exec, exec, vcc
	ds_read_b128 v[202:205], v193
	ds_read_b128 v[208:211], v193 offset:64
	ds_read_b128 v[212:215], v193 offset:128
	ds_read_b128 v[216:219], v193 offset:192
	ds_read_b128 v[220:223], v193 offset:256
	ds_read_b128 v[224:227], v193 offset:320
	s_waitcnt lgkmcnt(5)
	v_mfma_f32_16x16x32_bf16 v[100:103], v[202:205], v[96:99], 0
	ds_read_b128 v[202:205], v193 offset:384
	s_waitcnt lgkmcnt(5)
	v_mfma_f32_16x16x32_bf16 v[100:103], v[208:211], v[92:95], v[100:103]
	ds_read_b128 v[208:211], v193 offset:448
	s_waitcnt lgkmcnt(5)
	v_mfma_f32_16x16x32_bf16 v[100:103], v[212:215], v[88:91], v[100:103]
	ds_read_b128 v[212:215], v193 offset:8448
	s_waitcnt lgkmcnt(5)
	v_mfma_f32_16x16x32_bf16 v[100:103], v[216:219], v[84:87], v[100:103]
	ds_read_b128 v[216:219], v193 offset:8512
	s_waitcnt lgkmcnt(5)
	v_mfma_f32_16x16x32_bf16 v[100:103], v[220:223], v[80:83], v[100:103]
	ds_read_b128 v[220:223], v193 offset:8576
	s_waitcnt lgkmcnt(5)
	v_mfma_f32_16x16x32_bf16 v[100:103], v[224:227], v[76:79], v[100:103]
	s_waitcnt lgkmcnt(4)
	v_mfma_f32_16x16x32_bf16 v[100:103], v[202:205], v[72:75], v[100:103]
	ds_read_b128 v[202:205], v193 offset:8640
	s_waitcnt lgkmcnt(4)
	v_mfma_f32_16x16x32_bf16 v[100:103], v[208:211], v[68:71], v[100:103]
	ds_read_b128 v[208:211], v193 offset:8704
	s_waitcnt lgkmcnt(4)
	v_mfma_f32_16x16x32_bf16 v[224:227], v[212:215], v[96:99], 0
	ds_read_b128 v[212:215], v193 offset:8768
	s_waitcnt lgkmcnt(4)
	v_mfma_f32_16x16x32_bf16 v[224:227], v[216:219], v[92:95], v[224:227]
	ds_read_b128 v[216:219], v193 offset:8832
	s_waitcnt lgkmcnt(4)
	v_mfma_f32_16x16x32_bf16 v[224:227], v[220:223], v[88:91], v[224:227]
	ds_read_b128 v[220:223], v193 offset:8896
	s_waitcnt lgkmcnt(4)
	v_mfma_f32_16x16x32_bf16 v[224:227], v[202:205], v[84:87], v[224:227]
	s_waitcnt lgkmcnt(3)
	v_mfma_f32_16x16x32_bf16 v[224:227], v[208:211], v[80:83], v[224:227]
	s_waitcnt lgkmcnt(2)
	v_mfma_f32_16x16x32_bf16 v[224:227], v[212:215], v[76:79], v[224:227]
	s_waitcnt lgkmcnt(1)
	v_mfma_f32_16x16x32_bf16 v[224:227], v[216:219], v[72:75], v[224:227]
	s_waitcnt lgkmcnt(0)
	v_mfma_f32_16x16x32_bf16 v[68:71], v[220:223], v[68:71], v[224:227]
	s_nop 2
	ds_read_b128 v[72:75], v151
	ds_read_b128 v[76:79], v151 offset:16
	ds_read_b128 v[80:83], v151 offset:32
	ds_read_b128 v[84:87], v151 offset:48
	ds_read_b128 v[88:91], v152
	ds_read_b128 v[92:95], v152 offset:16
	ds_read_b128 v[96:99], v152 offset:32
	ds_read_b128 v[202:205], v152 offset:48
	s_waitcnt lgkmcnt(7)
	v_lshlrev_b32_e32 v201, 16, v72
	v_and_b32_e32 v72, 0xffff0000, v72
	s_waitcnt lgkmcnt(3)
	v_mul_f32_e32 v72, v89, v72
	v_fmac_f32_e32 v72, v88, v201
	v_lshlrev_b32_e32 v88, 16, v73
	v_fmac_f32_e32 v72, v90, v88
	v_and_b32_e32 v73, 0xffff0000, v73
	v_fmac_f32_e32 v72, v91, v73
	v_lshlrev_b32_e32 v73, 16, v74
	s_waitcnt lgkmcnt(2)
	v_fmac_f32_e32 v72, v92, v73
	v_and_b32_e32 v73, 0xffff0000, v74
	v_fmac_f32_e32 v72, v93, v73
	v_lshlrev_b32_e32 v73, 16, v75
	v_fmac_f32_e32 v72, v94, v73
	v_and_b32_e32 v73, 0xffff0000, v75
	v_and_b32_e32 v74, 0xffff0000, v76
	v_fmac_f32_e32 v72, v95, v73
	v_lshlrev_b32_e32 v73, 16, v76
	s_waitcnt lgkmcnt(1)
	v_mul_f32_e32 v74, v97, v74
	v_fmac_f32_e32 v74, v96, v73
	v_lshlrev_b32_e32 v73, 16, v77
	v_fmac_f32_e32 v74, v98, v73
	v_and_b32_e32 v73, 0xffff0000, v77
	v_fmac_f32_e32 v74, v99, v73
	v_lshlrev_b32_e32 v73, 16, v78
	s_waitcnt lgkmcnt(0)
	v_fmac_f32_e32 v74, v202, v73
	v_and_b32_e32 v73, 0xffff0000, v78
	v_fmac_f32_e32 v74, v203, v73
	v_lshlrev_b32_e32 v73, 16, v79
	v_fmac_f32_e32 v74, v204, v73
	v_and_b32_e32 v73, 0xffff0000, v79
	v_add_f32_e32 v72, 0, v72
	v_fmac_f32_e32 v74, v205, v73
	v_add_f32_e32 v88, v72, v74
	ds_read_b128 v[72:75], v152 offset:64
	ds_read_b128 v[76:79], v152 offset:80
	v_lshlrev_b32_e32 v89, 16, v80
	v_and_b32_e32 v80, 0xffff0000, v80
	s_waitcnt lgkmcnt(1)
	v_mul_f32_e32 v73, v73, v80
	v_fmac_f32_e32 v73, v72, v89
	v_lshlrev_b32_e32 v72, 16, v81
	v_fmac_f32_e32 v73, v74, v72
	v_and_b32_e32 v72, 0xffff0000, v81
	v_fmac_f32_e32 v73, v75, v72
	v_lshlrev_b32_e32 v72, 16, v82
	s_waitcnt lgkmcnt(0)
	v_fmac_f32_e32 v73, v76, v72
	v_and_b32_e32 v72, 0xffff0000, v82
	v_fmac_f32_e32 v73, v77, v72
	v_lshlrev_b32_e32 v72, 16, v83
	v_fmac_f32_e32 v73, v78, v72
	v_and_b32_e32 v72, 0xffff0000, v83
	v_fmac_f32_e32 v73, v79, v72
	v_add_f32_e32 v80, v88, v73
	ds_read_b128 v[72:75], v152 offset:96
	ds_read_b128 v[76:79], v152 offset:112
	v_and_b32_e32 v82, 0xffff0000, v84
	v_lshlrev_b32_e32 v81, 16, v84
	s_waitcnt lgkmcnt(1)
	v_mul_f32_e32 v73, v73, v82
	v_fmac_f32_e32 v73, v72, v81
	v_lshlrev_b32_e32 v72, 16, v85
	v_fmac_f32_e32 v73, v74, v72
	v_and_b32_e32 v72, 0xffff0000, v85
	v_fmac_f32_e32 v73, v75, v72
	v_lshlrev_b32_e32 v72, 16, v86
	s_waitcnt lgkmcnt(0)
	v_fmac_f32_e32 v73, v76, v72
	v_and_b32_e32 v72, 0xffff0000, v86
	v_fmac_f32_e32 v73, v77, v72
	v_lshlrev_b32_e32 v72, 16, v87
	v_fmac_f32_e32 v73, v78, v72
	v_and_b32_e32 v72, 0xffff0000, v87
	v_fmac_f32_e32 v73, v79, v72
	v_add_f32_e32 v72, v80, v73
	ds_bpermute_b32 v73, v153, v72
	s_waitcnt lgkmcnt(0)
	v_add_f32_e32 v72, v72, v73
	ds_bpermute_b32 v73, v154, v72
	s_waitcnt lgkmcnt(0)
	v_add_f32_e32 v72, v72, v73
	ds_bpermute_b32 v73, v155, v72
	s_and_saveexec_b64 s[72:73], s[10:11]
	s_cbranch_execz .LBB0_399
	s_waitcnt lgkmcnt(0)
	v_add_f32_e32 v72, v72, v73
	ds_write_b32 v157, v72
